# fp8 GEMMs: the unit-scale (2^0) block-scaled MFMA form replaced by the unscaled v_mfma_f32_16x16x128_f8f6f4 (same fp8 e4m3 operands, same f32 accumulate, no scale-load op)
# speedup vs baseline: 1.0052x; 1.0041x over previous
; #define PG8_STAGE(bufoff, gbase, voff) do { _Pragma("unroll") for (int _i = 0; _i < 2; ++_i) \
;         __builtin_amdgcn_global_load_lds((const unsigned*)((const char*)(gbase) + (voff)[_i]), (PG8_LAS unsigned*)(lds + (bufoff) + ldsw + _i * 8192), 16, 0, 0); } while (0)
; #define PG8_WAIT_V(n) asm volatile("s_waitcnt vmcnt(" #n ")" ::: "memory")
; #define PG8_WAIT_L(n) asm volatile("s_waitcnt lgkmcnt(" #n ")" ::: "memory")
; #define PG8_BAR __builtin_amdgcn_s_barrier()
; #define PG8_SCHED __builtin_amdgcn_sched_barrier(0)
; template <class Epi, class Sched, bool ALIGN_EPI = false, bool SP2 = false, bool F8 = false>
; __device__ __forceinline__ void gemm_phase(PG8_LAS unsigned char* lds, const Gemm g, const Sched& S, const Epi& E) {
;     ...
;         const bool has_next = S.next(ui + 1, nxt);
;         const char* nA = has_next ? (const char*)g.A + (size_t)nxt.pm * tstep : cA; const char* nB = has_next ? (const char*)g.Bt + (size_t)nxt.pn * tstep : cB;
;         for (int t = 0; t < nt; t += 2) {
;             const bool last = (t == nt - 2);
;             const char* a1 = cA + (size_t)(t + 1) * kstep;
;             const char* a2 = last ? nA : cA + (size_t)(t + 2) * kstep; const char* b2 = last ? nB : cB + (size_t)(t + 2) * kstep;
;             const char* a3 = a2 + kstep; const char* b3 = b2 + kstep;
;             if (last && has_next) S.a_ready(nxt);
;             if constexpr (SP2) {
;             PG8_LDB(B0, 0, 0); PG8_LDB(B1, 0, 1); PG8_SCHED; PG8_LDA(At, 0, 0); PG8_STAGE(PG8_SA(1, 1), a1 + hstep, voffA);
;             PG8_WAIT_V(8); PG8_WAIT_L(0); PG8_BAR; PG8_MMA(0, 0, At, B0); PG8_MMA(0, 1, At, B1); PG8_BAR; PG8_SCHED;
;             PG8_LDA(At, 0, 1); PG8_STAGE(PG8_SB(0, 0), b2, voffB); PG8_STAGE(PG8_SB(0, 1), b2 + hstep, voffB); PG8_STAGE(PG8_SA(0, 0), a2, voffA);
;             PG8_WAIT_V(8); PG8_WAIT_L(0); PG8_BAR; PG8_MMA(1, 0, At, B0); PG8_MMA(1, 1, At, B1); PG8_BAR; PG8_SCHED;
.LBB0_1021:
	s_ashr_i32 s17, s16, 31
	s_lshl_b64 s[36:37], s[16:17], 19
	v_readlane_b32 s11, v253, 59
	s_add_u32 s36, s11, s36
	v_readlane_b32 s11, v253, 60
	s_addc_u32 s37, s11, s37
	s_and_b64 s[42:43], s[38:39], exec
	s_cselect_b32 s17, s37, s41
	s_cselect_b32 s50, s36, s40
	s_ashr_i32 s11, s10, 31
	s_lshl_b64 s[42:43], s[10:11], 19
	s_add_u32 s42, s13, s42
	s_addc_u32 s43, s19, s43
	s_and_b64 s[46:47], s[38:39], exec
	s_cselect_b32 s11, s43, s45
	s_cselect_b32 s51, s42, s44
	s_add_u32 s40, s40, 0x40080
	s_addc_u32 s41, s41, 0
	s_add_u32 s52, s44, 0x100
	s_addc_u32 s53, s45, 0
	s_mov_b32 s54, -2
	s_add_u32 s44, s40, 0xfffc0080
	s_addc_u32 s45, s41, -1
	s_add_i32 s55, 0, 0x10000
	s_cmp_eq_u32 s54, 12
	s_cselect_b32 s47, s17, s45
	s_cselect_b32 s46, s50, s44
	s_cselect_b32 s45, s11, s53
	s_cselect_b32 s44, s51, s52
	s_add_i32 s56, 0, 0x14000
	v_add_u32_e32 v0, s55, v215
	v_add_u32_e32 v12, s56, v215
	ds_read_b128 v[16:19], v0
	ds_read_b128 v[20:23], v0 offset:1024
	ds_read_b128 v[24:27], v0 offset:2048
	ds_read_b128 v[28:31], v0 offset:3072
	ds_read_b128 v[0:3], v12
	ds_read_b128 v[4:7], v12 offset:1024
	ds_read_b128 v[8:11], v12 offset:2048
	ds_read_b128 v[12:15], v12 offset:3072
	v_lshl_add_u64 v[242:243], s[40:41], 0, v[192:193]
	s_add_i32 m0, s23, 0xc000
	ds_read_b128 v[196:199], v217
	ds_read_b128 v[200:203], v217 offset:1024
	ds_read_b128 v[218:221], v217 offset:2048
	ds_read_b128 v[222:225], v217 offset:3072
	ds_read_b128 v[226:229], v217 offset:4096
	ds_read_b128 v[230:233], v217 offset:5120
	ds_read_b128 v[234:237], v217 offset:6144
	ds_read_b128 v[238:241], v217 offset:7168
	global_load_lds_dwordx4 v[242:243], off
	v_lshl_add_u64 v[242:243], s[40:41], 0, v[194:195]
	s_add_i32 m0, s23, 0xe000
	s_nop 0
	global_load_lds_dwordx4 v[242:243], off
	s_waitcnt vmcnt(8)
	s_waitcnt lgkmcnt(0)
	s_barrier
	s_setprio 1
	s_waitcnt lgkmcnt(0)
	v_mfma_f32_16x16x128_f8f6f4 v[156:159], v[16:23], v[196:203], 0
	v_mfma_f32_16x16x128_f8f6f4 v[152:155], v[24:31], v[196:203], 0
	v_mfma_f32_16x16x128_f8f6f4 v[140:143], v[16:23], v[218:225], 0
	v_mfma_f32_16x16x128_f8f6f4 v[136:139], v[24:31], v[218:225], 0
	v_mfma_f32_16x16x128_f8f6f4 v[124:127], v[16:23], v[226:233], 0
	v_mfma_f32_16x16x128_f8f6f4 v[120:123], v[24:31], v[226:233], 0
	v_mfma_f32_16x16x128_f8f6f4 v[108:111], v[16:23], v[234:241], 0
	v_mfma_f32_16x16x128_f8f6f4 v[104:107], v[24:31], v[234:241], 0
	s_setprio 0
	s_setprio 1
	v_mfma_f32_16x16x128_f8f6f4 v[148:151], v[0:7], v[196:203], 0
	v_mfma_f32_16x16x128_f8f6f4 v[144:147], v[8:15], v[196:203], 0
	v_mfma_f32_16x16x128_f8f6f4 v[132:135], v[0:7], v[218:225], 0
	v_mfma_f32_16x16x128_f8f6f4 v[128:131], v[8:15], v[218:225], 0
	v_mfma_f32_16x16x128_f8f6f4 v[116:119], v[0:7], v[226:233], 0
	v_mfma_f32_16x16x128_f8f6f4 v[112:115], v[8:15], v[226:233], 0
	v_mfma_f32_16x16x128_f8f6f4 v[100:103], v[0:7], v[234:241], 0
	v_mfma_f32_16x16x128_f8f6f4 v[96:99], v[8:15], v[234:241], 0
	s_setprio 0
	s_barrier
	s_add_i32 s55, s55, s22
	v_lshl_add_u64 v[196:197], s[44:45], 0, v[188:189]
	s_mov_b32 m0, s55
	ds_read_b128 v[218:221], v217 offset:16384
	ds_read_b128 v[222:225], v217 offset:17408
	ds_read_b128 v[226:229], v217 offset:18432
	ds_read_b128 v[230:233], v217 offset:19456
	ds_read_b128 v[234:237], v217 offset:20480
	ds_read_b128 v[238:241], v217 offset:21504
	ds_read_b128 v[242:245], v217 offset:22528
	ds_read_b128 v[246:249], v217 offset:23552
	global_load_lds_dwordx4 v[196:197], off
	s_add_i32 m0, s55, 0x2000
	s_add_u32 s58, s44, 0x40000
	v_lshl_add_u64 v[198:199], s[44:45], 0, v[184:185]
	s_addc_u32 s59, s45, 0
	s_add_i32 s55, s56, s22
	global_load_lds_dwordx4 v[198:199], off
	v_lshl_add_u64 v[200:201], s[58:59], 0, v[188:189]
	s_mov_b32 m0, s55
	v_lshl_add_u64 v[202:203], s[46:47], 0, v[186:187]
	global_load_lds_dwordx4 v[200:201], off
	v_lshl_add_u64 v[200:201], s[58:59], 0, v[184:185]
	s_add_i32 m0, s55, 0x2000
	s_nop 0
	global_load_lds_dwordx4 v[200:201], off
	v_lshl_add_u64 v[200:201], s[46:47], 0, v[190:191]
	s_mov_b32 m0, s23
	s_nop 0
	global_load_lds_dwordx4 v[200:201], off
	s_mov_b32 m0, s8
	s_nop 0
	global_load_lds_dwordx4 v[202:203], off
	s_waitcnt vmcnt(8)
	s_waitcnt lgkmcnt(0)
	s_barrier
	s_setprio 1
	s_waitcnt lgkmcnt(0)
	v_mfma_f32_16x16x128_f8f6f4 v[92:95], v[16:23], v[218:225], 0
	v_mfma_f32_16x16x128_f8f6f4 v[88:91], v[24:31], v[218:225], 0
	v_mfma_f32_16x16x128_f8f6f4 v[76:79], v[16:23], v[226:233], 0
	v_mfma_f32_16x16x128_f8f6f4 v[72:75], v[24:31], v[226:233], 0
	v_mfma_f32_16x16x128_f8f6f4 v[60:63], v[16:23], v[234:241], 0
	v_mfma_f32_16x16x128_f8f6f4 v[56:59], v[24:31], v[234:241], 0
	v_mfma_f32_16x16x128_f8f6f4 v[44:47], v[16:23], v[242:249], 0
	v_mfma_f32_16x16x128_f8f6f4 v[40:43], v[24:31], v[242:249], 0
	s_setprio 0
	s_setprio 1
	v_mfma_f32_16x16x128_f8f6f4 v[84:87], v[0:7], v[218:225], 0
	v_mfma_f32_16x16x128_f8f6f4 v[80:83], v[8:15], v[218:225], 0
	v_mfma_f32_16x16x128_f8f6f4 v[68:71], v[0:7], v[226:233], 0
	v_mfma_f32_16x16x128_f8f6f4 v[64:67], v[8:15], v[226:233], 0
	v_mfma_f32_16x16x128_f8f6f4 v[52:55], v[0:7], v[234:241], 0
	v_mfma_f32_16x16x128_f8f6f4 v[48:51], v[8:15], v[234:241], 0
	v_mfma_f32_16x16x128_f8f6f4 v[36:39], v[0:7], v[242:249], 0
	v_mfma_f32_16x16x128_f8f6f4 v[32:35], v[8:15], v[242:249], 0
	s_setprio 0
	s_barrier
; #define PG8_STAGE(bufoff, gbase, voff) do { _Pragma("unroll") for (int _i = 0; _i < 2; ++_i) \
;         __builtin_amdgcn_global_load_lds((const unsigned*)((const char*)(gbase) + (voff)[_i]), (PG8_LAS unsigned*)(lds + (bufoff) + ldsw + _i * 8192), 16, 0, 0); } while (0)
; #define PG8_WAIT_V(n) asm volatile("s_waitcnt vmcnt(" #n ")" ::: "memory")
; #define PG8_WAIT_L(n) asm volatile("s_waitcnt lgkmcnt(" #n ")" ::: "memory")
; #define PG8_BAR __builtin_amdgcn_s_barrier()
; #define PG8_SCHED __builtin_amdgcn_sched_barrier(0)
; template <class Epi, class Sched, bool ALIGN_EPI = false, bool SP2 = false, bool F8 = false>
; __device__ __forceinline__ void gemm_phase(PG8_LAS unsigned char* lds, const Gemm g, const Sched& S, const Epi& E) {
;     ...
;         for (int t = 0; t < nt; t += 2) {
;     ...
;             PG8_LDB(B0, 1, 0); PG8_LDB(B1, 1, 1); PG8_SCHED; PG8_LDA(At, 1, 0); PG8_STAGE(PG8_SA(0, 1), a2 + hstep, voffA);
;             PG8_WAIT_V(8); PG8_WAIT_L(0); PG8_BAR; PG8_MMA(0, 0, At, B0); PG8_MMA(0, 1, At, B1); PG8_BAR; PG8_SCHED;
;             PG8_LDA(At, 1, 1); PG8_STAGE(PG8_SB(1, 0), b3, voffB); PG8_STAGE(PG8_SB(1, 1), b3 + hstep, voffB); PG8_STAGE(PG8_SA(1, 0), a3, voffA);
;             PG8_WAIT_V(8); PG8_WAIT_L(0); PG8_BAR; PG8_MMA(1, 0, At, B0); PG8_MMA(1, 1, At, B1); PG8_BAR; PG8_SCHED;
	s_add_i32 s55, 0, 0x18000
	s_add_i32 s56, 0, 0x1c000
	v_add_u32_e32 v12, s55, v215
	v_add_u32_e32 v28, s56, v215
	ds_read_b128 v[0:3], v12
	ds_read_b128 v[4:7], v12 offset:1024
	ds_read_b128 v[8:11], v12 offset:2048
	ds_read_b128 v[12:15], v12 offset:3072
	ds_read_b128 v[16:19], v28
	ds_read_b128 v[20:23], v28 offset:1024
	ds_read_b128 v[24:27], v28 offset:2048
	ds_read_b128 v[28:31], v28 offset:3072
	s_add_u32 s46, s46, 0x40000
	s_addc_u32 s47, s47, 0
	s_mov_b32 m0, s9
	v_lshl_add_u64 v[162:163], s[46:47], 0, v[190:191]
	ds_read_b128 v[218:221], v217 offset:32768
	ds_read_b128 v[222:225], v217 offset:33792
	ds_read_b128 v[226:229], v217 offset:34816
	ds_read_b128 v[230:233], v217 offset:35840
	ds_read_b128 v[234:237], v217 offset:36864
	ds_read_b128 v[238:241], v217 offset:37888
	ds_read_b128 v[242:245], v217 offset:38912
	ds_read_b128 v[246:249], v217 offset:39936
	global_load_lds_dwordx4 v[162:163], off
	v_lshl_add_u64 v[162:163], s[46:47], 0, v[186:187]
	s_mov_b32 m0, s28
	s_nop 0
	global_load_lds_dwordx4 v[162:163], off
	s_waitcnt vmcnt(8)
	s_waitcnt lgkmcnt(0)
	s_barrier
	s_setprio 1
	s_waitcnt lgkmcnt(0)
	v_mfma_f32_16x16x128_f8f6f4 v[156:159], v[0:7], v[218:225], v[156:159]
	v_mfma_f32_16x16x128_f8f6f4 v[152:155], v[8:15], v[218:225], v[152:155]
	v_mfma_f32_16x16x128_f8f6f4 v[140:143], v[0:7], v[226:233], v[140:143]
	v_mfma_f32_16x16x128_f8f6f4 v[136:139], v[8:15], v[226:233], v[136:139]
	v_mfma_f32_16x16x128_f8f6f4 v[124:127], v[0:7], v[234:241], v[124:127]
	v_mfma_f32_16x16x128_f8f6f4 v[120:123], v[8:15], v[234:241], v[120:123]
	v_mfma_f32_16x16x128_f8f6f4 v[108:111], v[0:7], v[242:249], v[108:111]
	v_mfma_f32_16x16x128_f8f6f4 v[104:107], v[8:15], v[242:249], v[104:107]
	s_setprio 0
	s_setprio 1
	v_mfma_f32_16x16x128_f8f6f4 v[148:151], v[16:23], v[218:225], v[148:151]
	v_mfma_f32_16x16x128_f8f6f4 v[144:147], v[24:31], v[218:225], v[144:147]
	v_mfma_f32_16x16x128_f8f6f4 v[132:135], v[16:23], v[226:233], v[132:135]
	v_mfma_f32_16x16x128_f8f6f4 v[128:131], v[24:31], v[226:233], v[128:131]
	v_mfma_f32_16x16x128_f8f6f4 v[116:119], v[16:23], v[234:241], v[116:119]
	v_mfma_f32_16x16x128_f8f6f4 v[112:115], v[24:31], v[234:241], v[112:115]
	v_mfma_f32_16x16x128_f8f6f4 v[100:103], v[16:23], v[242:249], v[100:103]
	v_mfma_f32_16x16x128_f8f6f4 v[96:99], v[24:31], v[242:249], v[96:99]
	s_setprio 0
	s_barrier
	s_add_i32 s46, s55, s22
	v_lshl_add_u64 v[162:163], v[196:197], 0, s[14:15]
	s_mov_b32 m0, s46
	ds_read_b128 v[218:221], v217 offset:49152
	ds_read_b128 v[222:225], v217 offset:50176
	ds_read_b128 v[226:229], v217 offset:51200
	ds_read_b128 v[230:233], v217 offset:52224
	ds_read_b128 v[234:237], v217 offset:53248
	ds_read_b128 v[238:241], v217 offset:54272
	ds_read_b128 v[242:245], v217 offset:55296
	ds_read_b128 v[246:249], v217 offset:56320
	global_load_lds_dwordx4 v[162:163], off
	s_add_i32 m0, s46, 0x2000
	s_add_u32 s44, s44, 0x40080
	v_lshl_add_u64 v[162:163], v[198:199], 0, s[14:15]
	s_addc_u32 s45, s45, 0
	s_add_i32 s46, s56, s22
	global_load_lds_dwordx4 v[162:163], off
	v_lshl_add_u64 v[162:163], s[44:45], 0, v[188:189]
	s_mov_b32 m0, s46
	s_nop 0
	global_load_lds_dwordx4 v[162:163], off
	v_lshl_add_u64 v[162:163], s[44:45], 0, v[184:185]
	s_add_i32 m0, s46, 0x2000
	s_nop 0
	global_load_lds_dwordx4 v[162:163], off
	v_lshl_add_u64 v[162:163], v[200:201], 0, s[14:15]
	s_mov_b32 m0, s29
	s_nop 0
	global_load_lds_dwordx4 v[162:163], off
	v_lshl_add_u64 v[162:163], v[202:203], 0, s[14:15]
	s_mov_b32 m0, s48
	s_nop 0
	global_load_lds_dwordx4 v[162:163], off
	s_waitcnt vmcnt(8)
	s_waitcnt lgkmcnt(0)
	s_barrier
	s_setprio 1
	s_waitcnt lgkmcnt(0)
	v_mfma_f32_16x16x128_f8f6f4 v[92:95], v[0:7], v[218:225], v[92:95]
	v_mfma_f32_16x16x128_f8f6f4 v[88:91], v[8:15], v[218:225], v[88:91]
	v_mfma_f32_16x16x128_f8f6f4 v[76:79], v[0:7], v[226:233], v[76:79]
	v_mfma_f32_16x16x128_f8f6f4 v[72:75], v[8:15], v[226:233], v[72:75]
	v_mfma_f32_16x16x128_f8f6f4 v[60:63], v[0:7], v[234:241], v[60:63]
	v_mfma_f32_16x16x128_f8f6f4 v[56:59], v[8:15], v[234:241], v[56:59]
	v_mfma_f32_16x16x128_f8f6f4 v[44:47], v[0:7], v[242:249], v[44:47]
	v_mfma_f32_16x16x128_f8f6f4 v[40:43], v[8:15], v[242:249], v[40:43]
	s_setprio 0
	s_setprio 1
	v_mfma_f32_16x16x128_f8f6f4 v[84:87], v[16:23], v[218:225], v[84:87]
	v_mfma_f32_16x16x128_f8f6f4 v[80:83], v[24:31], v[218:225], v[80:83]
	v_mfma_f32_16x16x128_f8f6f4 v[68:71], v[16:23], v[226:233], v[68:71]
	v_mfma_f32_16x16x128_f8f6f4 v[64:67], v[24:31], v[226:233], v[64:67]
	v_mfma_f32_16x16x128_f8f6f4 v[52:55], v[16:23], v[234:241], v[52:55]
	v_mfma_f32_16x16x128_f8f6f4 v[48:51], v[24:31], v[234:241], v[48:51]
	v_mfma_f32_16x16x128_f8f6f4 v[36:39], v[16:23], v[242:249], v[36:39]
	v_mfma_f32_16x16x128_f8f6f4 v[32:35], v[24:31], v[242:249], v[32:35]
	s_setprio 0
	s_barrier
	s_add_i32 s54, s54, 2
	s_add_u32 s40, s40, 0x100
	s_addc_u32 s41, s41, 0
	s_add_u32 s52, s52, 0x100
	s_addc_u32 s53, s53, 0
	s_cmp_gt_u32 s54, 13
	s_cbranch_scc0 .LBB0_1022
	s_branch .Lgk_after_1022
; #define PG8_STAGE(bufoff, gbase, voff) do { _Pragma("unroll") for (int _i = 0; _i < 2; ++_i) \
;         __builtin_amdgcn_global_load_lds((const unsigned*)((const char*)(gbase) + (voff)[_i]), (PG8_LAS unsigned*)(lds + (bufoff) + ldsw + _i * 8192), 16, 0, 0); } while (0)
; #define PG8_WAIT_V(n) asm volatile("s_waitcnt vmcnt(" #n ")" ::: "memory")
; #define PG8_WAIT_L(n) asm volatile("s_waitcnt lgkmcnt(" #n ")" ::: "memory")
; #define PG8_BAR __builtin_amdgcn_s_barrier()
; #define PG8_SCHED __builtin_amdgcn_sched_barrier(0)
; template <class Epi, class Sched, bool ALIGN_EPI = false, bool SP2 = false, bool F8 = false>
; __device__ __forceinline__ void gemm_phase(PG8_LAS unsigned char* lds, const Gemm g, const Sched& S, const Epi& E) {
;     ...
;             const bool last = (t == nt - 2);
;             const char* a1 = cA + (size_t)(t + 1) * kstep;
;             const char* a2 = last ? nA : cA + (size_t)(t + 2) * kstep; const char* b2 = last ? nB : cB + (size_t)(t + 2) * kstep;
;             const char* a3 = a2 + kstep; const char* b3 = b2 + kstep;
;             if (last && has_next) S.a_ready(nxt);
;             if constexpr (SP2) {
;             PG8_LDB(B0, 0, 0); PG8_LDB(B1, 0, 1); PG8_SCHED; PG8_LDA(At, 0, 0); PG8_STAGE(PG8_SA(1, 1), a1 + hstep, voffA);
;             PG8_WAIT_V(8); PG8_WAIT_L(0); PG8_BAR; PG8_MMA(0, 0, At, B0); PG8_MMA(0, 1, At, B1); PG8_BAR; PG8_SCHED;
;             PG8_LDA(At, 0, 1); PG8_STAGE(PG8_SB(0, 0), b2, voffB); PG8_STAGE(PG8_SB(0, 1), b2 + hstep, voffB); PG8_STAGE(PG8_SA(0, 0), a2, voffA);
;             PG8_WAIT_V(8); PG8_WAIT_L(0); PG8_BAR; PG8_MMA(1, 0, At, B0); PG8_MMA(1, 1, At, B1); PG8_BAR; PG8_SCHED;
.LBB0_1022:
	s_add_u32 s44, s40, 0xfffc0080
	s_addc_u32 s45, s41, -1
	s_add_i32 s55, 0, 0x10000
	s_cmp_eq_u32 s54, 12
	s_cselect_b32 s47, s17, s45
	s_cselect_b32 s46, s50, s44
	s_cselect_b32 s45, s11, s53
	s_cselect_b32 s44, s51, s52
	s_add_i32 s56, 0, 0x14000
	v_add_u32_e32 v0, s55, v215
	v_add_u32_e32 v12, s56, v215
	ds_read_b128 v[16:19], v0
	ds_read_b128 v[20:23], v0 offset:1024
	ds_read_b128 v[24:27], v0 offset:2048
	ds_read_b128 v[28:31], v0 offset:3072
	ds_read_b128 v[0:3], v12
	ds_read_b128 v[4:7], v12 offset:1024
	ds_read_b128 v[8:11], v12 offset:2048
	ds_read_b128 v[12:15], v12 offset:3072
	v_lshl_add_u64 v[242:243], s[40:41], 0, v[192:193]
	s_add_i32 m0, s23, 0xc000
	ds_read_b128 v[196:199], v217
	ds_read_b128 v[200:203], v217 offset:1024
	ds_read_b128 v[218:221], v217 offset:2048
	ds_read_b128 v[222:225], v217 offset:3072
	ds_read_b128 v[226:229], v217 offset:4096
	ds_read_b128 v[230:233], v217 offset:5120
	ds_read_b128 v[234:237], v217 offset:6144
	ds_read_b128 v[238:241], v217 offset:7168
	global_load_lds_dwordx4 v[242:243], off
	v_lshl_add_u64 v[242:243], s[40:41], 0, v[194:195]
	s_add_i32 m0, s23, 0xe000
	s_nop 0
	global_load_lds_dwordx4 v[242:243], off
	s_waitcnt vmcnt(8)
	s_waitcnt lgkmcnt(0)
	s_barrier
	s_setprio 1
	s_waitcnt lgkmcnt(0)
	v_mfma_f32_16x16x128_f8f6f4 v[156:159], v[16:23], v[196:203], v[156:159]
	v_mfma_f32_16x16x128_f8f6f4 v[152:155], v[24:31], v[196:203], v[152:155]
	v_mfma_f32_16x16x128_f8f6f4 v[140:143], v[16:23], v[218:225], v[140:143]
	v_mfma_f32_16x16x128_f8f6f4 v[136:139], v[24:31], v[218:225], v[136:139]
	v_mfma_f32_16x16x128_f8f6f4 v[124:127], v[16:23], v[226:233], v[124:127]
	v_mfma_f32_16x16x128_f8f6f4 v[120:123], v[24:31], v[226:233], v[120:123]
	v_mfma_f32_16x16x128_f8f6f4 v[108:111], v[16:23], v[234:241], v[108:111]
	v_mfma_f32_16x16x128_f8f6f4 v[104:107], v[24:31], v[234:241], v[104:107]
	s_setprio 0
	s_setprio 1
	v_mfma_f32_16x16x128_f8f6f4 v[148:151], v[0:7], v[196:203], v[148:151]
	v_mfma_f32_16x16x128_f8f6f4 v[144:147], v[8:15], v[196:203], v[144:147]
	v_mfma_f32_16x16x128_f8f6f4 v[132:135], v[0:7], v[218:225], v[132:135]
	v_mfma_f32_16x16x128_f8f6f4 v[128:131], v[8:15], v[218:225], v[128:131]
	v_mfma_f32_16x16x128_f8f6f4 v[116:119], v[0:7], v[226:233], v[116:119]
	v_mfma_f32_16x16x128_f8f6f4 v[112:115], v[8:15], v[226:233], v[112:115]
	v_mfma_f32_16x16x128_f8f6f4 v[100:103], v[0:7], v[234:241], v[100:103]
	v_mfma_f32_16x16x128_f8f6f4 v[96:99], v[8:15], v[234:241], v[96:99]
	s_setprio 0
	s_barrier
	s_add_i32 s55, s55, s22
	v_lshl_add_u64 v[196:197], s[44:45], 0, v[188:189]
	s_mov_b32 m0, s55
	ds_read_b128 v[218:221], v217 offset:16384
	ds_read_b128 v[222:225], v217 offset:17408
	ds_read_b128 v[226:229], v217 offset:18432
	ds_read_b128 v[230:233], v217 offset:19456
	ds_read_b128 v[234:237], v217 offset:20480
	ds_read_b128 v[238:241], v217 offset:21504
	ds_read_b128 v[242:245], v217 offset:22528
	ds_read_b128 v[246:249], v217 offset:23552
	global_load_lds_dwordx4 v[196:197], off
	s_add_i32 m0, s55, 0x2000
	s_add_u32 s58, s44, 0x40000
	v_lshl_add_u64 v[198:199], s[44:45], 0, v[184:185]
	s_addc_u32 s59, s45, 0
	s_add_i32 s55, s56, s22
	global_load_lds_dwordx4 v[198:199], off
	v_lshl_add_u64 v[200:201], s[58:59], 0, v[188:189]
	s_mov_b32 m0, s55
	v_lshl_add_u64 v[202:203], s[46:47], 0, v[186:187]
	global_load_lds_dwordx4 v[200:201], off
	v_lshl_add_u64 v[200:201], s[58:59], 0, v[184:185]
	s_add_i32 m0, s55, 0x2000
	s_nop 0
	global_load_lds_dwordx4 v[200:201], off
	v_lshl_add_u64 v[200:201], s[46:47], 0, v[190:191]
	s_mov_b32 m0, s23
	s_nop 0
	global_load_lds_dwordx4 v[200:201], off
	s_mov_b32 m0, s8
	s_nop 0
	global_load_lds_dwordx4 v[202:203], off
	s_waitcnt vmcnt(8)
	s_waitcnt lgkmcnt(0)
	s_barrier
	s_setprio 1
	s_waitcnt lgkmcnt(0)
	v_mfma_f32_16x16x128_f8f6f4 v[92:95], v[16:23], v[218:225], v[92:95]
	v_mfma_f32_16x16x128_f8f6f4 v[88:91], v[24:31], v[218:225], v[88:91]
	v_mfma_f32_16x16x128_f8f6f4 v[76:79], v[16:23], v[226:233], v[76:79]
	v_mfma_f32_16x16x128_f8f6f4 v[72:75], v[24:31], v[226:233], v[72:75]
	v_mfma_f32_16x16x128_f8f6f4 v[60:63], v[16:23], v[234:241], v[60:63]
	v_mfma_f32_16x16x128_f8f6f4 v[56:59], v[24:31], v[234:241], v[56:59]
	v_mfma_f32_16x16x128_f8f6f4 v[44:47], v[16:23], v[242:249], v[44:47]
	v_mfma_f32_16x16x128_f8f6f4 v[40:43], v[24:31], v[242:249], v[40:43]
	s_setprio 0
	s_setprio 1
	v_mfma_f32_16x16x128_f8f6f4 v[84:87], v[0:7], v[218:225], v[84:87]
	v_mfma_f32_16x16x128_f8f6f4 v[80:83], v[8:15], v[218:225], v[80:83]
	v_mfma_f32_16x16x128_f8f6f4 v[68:71], v[0:7], v[226:233], v[68:71]
	v_mfma_f32_16x16x128_f8f6f4 v[64:67], v[8:15], v[226:233], v[64:67]
	v_mfma_f32_16x16x128_f8f6f4 v[52:55], v[0:7], v[234:241], v[52:55]
	v_mfma_f32_16x16x128_f8f6f4 v[48:51], v[8:15], v[234:241], v[48:51]
	v_mfma_f32_16x16x128_f8f6f4 v[36:39], v[0:7], v[242:249], v[36:39]
	v_mfma_f32_16x16x128_f8f6f4 v[32:35], v[8:15], v[242:249], v[32:35]
	s_setprio 0
	s_barrier
; #define PG8_STAGE(bufoff, gbase, voff) do { _Pragma("unroll") for (int _i = 0; _i < 2; ++_i) \
;         __builtin_amdgcn_global_load_lds((const unsigned*)((const char*)(gbase) + (voff)[_i]), (PG8_LAS unsigned*)(lds + (bufoff) + ldsw + _i * 8192), 16, 0, 0); } while (0)
; #define PG8_WAIT_V(n) asm volatile("s_waitcnt vmcnt(" #n ")" ::: "memory")
; #define PG8_WAIT_L(n) asm volatile("s_waitcnt lgkmcnt(" #n ")" ::: "memory")
; #define PG8_BAR __builtin_amdgcn_s_barrier()
; #define PG8_SCHED __builtin_amdgcn_sched_barrier(0)
; template <class Epi, class Sched, bool ALIGN_EPI = false, bool SP2 = false, bool F8 = false>
; __device__ __forceinline__ void gemm_phase(PG8_LAS unsigned char* lds, const Gemm g, const Sched& S, const Epi& E) {
;     ...
;             PG8_LDB(B0, 1, 0); PG8_LDB(B1, 1, 1); PG8_SCHED; PG8_LDA(At, 1, 0); PG8_STAGE(PG8_SA(0, 1), a2 + hstep, voffA);
;             PG8_WAIT_V(8); PG8_WAIT_L(0); PG8_BAR; PG8_MMA(0, 0, At, B0); PG8_MMA(0, 1, At, B1); PG8_BAR; PG8_SCHED;
;             PG8_LDA(At, 1, 1); PG8_STAGE(PG8_SB(1, 0), b3, voffB); PG8_STAGE(PG8_SB(1, 1), b3 + hstep, voffB); PG8_STAGE(PG8_SA(1, 0), a3, voffA);
;             PG8_WAIT_V(8); PG8_WAIT_L(0); PG8_BAR; PG8_MMA(1, 0, At, B0); PG8_MMA(1, 1, At, B1); PG8_BAR; PG8_SCHED;
	s_add_i32 s55, 0, 0x18000
	s_add_i32 s56, 0, 0x1c000
	v_add_u32_e32 v12, s55, v215
	v_add_u32_e32 v28, s56, v215
	ds_read_b128 v[0:3], v12
	ds_read_b128 v[4:7], v12 offset:1024
	ds_read_b128 v[8:11], v12 offset:2048
	ds_read_b128 v[12:15], v12 offset:3072
	ds_read_b128 v[16:19], v28
	ds_read_b128 v[20:23], v28 offset:1024
	ds_read_b128 v[24:27], v28 offset:2048
	ds_read_b128 v[28:31], v28 offset:3072
	s_add_u32 s46, s46, 0x40000
	s_addc_u32 s47, s47, 0
	s_mov_b32 m0, s9
	v_lshl_add_u64 v[162:163], s[46:47], 0, v[190:191]
	ds_read_b128 v[218:221], v217 offset:32768
	ds_read_b128 v[222:225], v217 offset:33792
	ds_read_b128 v[226:229], v217 offset:34816
	ds_read_b128 v[230:233], v217 offset:35840
	ds_read_b128 v[234:237], v217 offset:36864
	ds_read_b128 v[238:241], v217 offset:37888
	ds_read_b128 v[242:245], v217 offset:38912
	ds_read_b128 v[246:249], v217 offset:39936
	global_load_lds_dwordx4 v[162:163], off
	v_lshl_add_u64 v[162:163], s[46:47], 0, v[186:187]
	s_mov_b32 m0, s28
	s_nop 0
	global_load_lds_dwordx4 v[162:163], off
	s_waitcnt vmcnt(8)
	s_waitcnt lgkmcnt(0)
	s_barrier
	s_setprio 1
	s_waitcnt lgkmcnt(0)
	v_mfma_f32_16x16x128_f8f6f4 v[156:159], v[0:7], v[218:225], v[156:159]
	v_mfma_f32_16x16x128_f8f6f4 v[152:155], v[8:15], v[218:225], v[152:155]
	v_mfma_f32_16x16x128_f8f6f4 v[140:143], v[0:7], v[226:233], v[140:143]
	v_mfma_f32_16x16x128_f8f6f4 v[136:139], v[8:15], v[226:233], v[136:139]
	v_mfma_f32_16x16x128_f8f6f4 v[124:127], v[0:7], v[234:241], v[124:127]
	v_mfma_f32_16x16x128_f8f6f4 v[120:123], v[8:15], v[234:241], v[120:123]
	v_mfma_f32_16x16x128_f8f6f4 v[108:111], v[0:7], v[242:249], v[108:111]
	v_mfma_f32_16x16x128_f8f6f4 v[104:107], v[8:15], v[242:249], v[104:107]
	s_setprio 0
	s_setprio 1
	v_mfma_f32_16x16x128_f8f6f4 v[148:151], v[16:23], v[218:225], v[148:151]
	v_mfma_f32_16x16x128_f8f6f4 v[144:147], v[24:31], v[218:225], v[144:147]
	v_mfma_f32_16x16x128_f8f6f4 v[132:135], v[16:23], v[226:233], v[132:135]
	v_mfma_f32_16x16x128_f8f6f4 v[128:131], v[24:31], v[226:233], v[128:131]
	v_mfma_f32_16x16x128_f8f6f4 v[116:119], v[16:23], v[234:241], v[116:119]
	v_mfma_f32_16x16x128_f8f6f4 v[112:115], v[24:31], v[234:241], v[112:115]
	v_mfma_f32_16x16x128_f8f6f4 v[100:103], v[16:23], v[242:249], v[100:103]
	v_mfma_f32_16x16x128_f8f6f4 v[96:99], v[24:31], v[242:249], v[96:99]
	s_setprio 0
	s_barrier
	s_add_i32 s46, s55, s22
	v_lshl_add_u64 v[162:163], v[196:197], 0, s[14:15]
	s_mov_b32 m0, s46
	ds_read_b128 v[218:221], v217 offset:49152
	ds_read_b128 v[222:225], v217 offset:50176
	ds_read_b128 v[226:229], v217 offset:51200
	ds_read_b128 v[230:233], v217 offset:52224
	ds_read_b128 v[234:237], v217 offset:53248
	ds_read_b128 v[238:241], v217 offset:54272
	ds_read_b128 v[242:245], v217 offset:55296
	ds_read_b128 v[246:249], v217 offset:56320
	global_load_lds_dwordx4 v[162:163], off
	s_add_i32 m0, s46, 0x2000
	s_add_u32 s44, s44, 0x40080
	v_lshl_add_u64 v[162:163], v[198:199], 0, s[14:15]
	s_addc_u32 s45, s45, 0
	s_add_i32 s46, s56, s22
	global_load_lds_dwordx4 v[162:163], off
	v_lshl_add_u64 v[162:163], s[44:45], 0, v[188:189]
	s_mov_b32 m0, s46
	s_nop 0
	global_load_lds_dwordx4 v[162:163], off
	v_lshl_add_u64 v[162:163], s[44:45], 0, v[184:185]
	s_add_i32 m0, s46, 0x2000
	s_nop 0
	global_load_lds_dwordx4 v[162:163], off
	v_lshl_add_u64 v[162:163], v[200:201], 0, s[14:15]
	s_mov_b32 m0, s29
	s_nop 0
	global_load_lds_dwordx4 v[162:163], off
	v_lshl_add_u64 v[162:163], v[202:203], 0, s[14:15]
	s_mov_b32 m0, s48
	s_nop 0
	global_load_lds_dwordx4 v[162:163], off
	s_waitcnt vmcnt(8)
	s_waitcnt lgkmcnt(0)
	s_barrier
	s_setprio 1
	s_waitcnt lgkmcnt(0)
	v_mfma_f32_16x16x128_f8f6f4 v[92:95], v[0:7], v[218:225], v[92:95]
	v_mfma_f32_16x16x128_f8f6f4 v[88:91], v[8:15], v[218:225], v[88:91]
	v_mfma_f32_16x16x128_f8f6f4 v[76:79], v[0:7], v[226:233], v[76:79]
	v_mfma_f32_16x16x128_f8f6f4 v[72:75], v[8:15], v[226:233], v[72:75]
	v_mfma_f32_16x16x128_f8f6f4 v[60:63], v[0:7], v[234:241], v[60:63]
	v_mfma_f32_16x16x128_f8f6f4 v[56:59], v[8:15], v[234:241], v[56:59]
	v_mfma_f32_16x16x128_f8f6f4 v[44:47], v[0:7], v[242:249], v[44:47]
	v_mfma_f32_16x16x128_f8f6f4 v[40:43], v[8:15], v[242:249], v[40:43]
	s_setprio 0
	s_setprio 1
	v_mfma_f32_16x16x128_f8f6f4 v[84:87], v[16:23], v[218:225], v[84:87]
	v_mfma_f32_16x16x128_f8f6f4 v[80:83], v[24:31], v[218:225], v[80:83]
	v_mfma_f32_16x16x128_f8f6f4 v[68:71], v[16:23], v[226:233], v[68:71]
	v_mfma_f32_16x16x128_f8f6f4 v[64:67], v[24:31], v[226:233], v[64:67]
	v_mfma_f32_16x16x128_f8f6f4 v[52:55], v[16:23], v[234:241], v[52:55]
	v_mfma_f32_16x16x128_f8f6f4 v[48:51], v[24:31], v[234:241], v[48:51]
	v_mfma_f32_16x16x128_f8f6f4 v[36:39], v[16:23], v[242:249], v[36:39]
	v_mfma_f32_16x16x128_f8f6f4 v[32:35], v[24:31], v[242:249], v[32:35]
	s_setprio 0
	s_barrier
	s_add_i32 s54, s54, 2
	s_add_u32 s40, s40, 0x100
	s_addc_u32 s41, s41, 0
	s_add_u32 s52, s52, 0x100
	s_addc_u32 s53, s53, 0
	s_cmp_gt_u32 s54, 13
	s_cbranch_scc0 .LBB0_1022

; #define PG8_STAGE(bufoff, gbase, voff) do { _Pragma("unroll") for (int _i = 0; _i < 2; ++_i) \
;         __builtin_amdgcn_global_load_lds((const unsigned*)((const char*)(gbase) + (voff)[_i]), (PG8_LAS unsigned*)(lds + (bufoff) + ldsw + _i * 8192), 16, 0, 0); } while (0)
; #define PG8_WAIT_V(n) asm volatile("s_waitcnt vmcnt(" #n ")" ::: "memory")
; #define PG8_WAIT_L(n) asm volatile("s_waitcnt lgkmcnt(" #n ")" ::: "memory")
; #define PG8_BAR __builtin_amdgcn_s_barrier()
; #define PG8_SCHED __builtin_amdgcn_sched_barrier(0)
; template <class Epi, class Sched, bool ALIGN_EPI = false, bool SP2 = false, bool F8 = false>
; __device__ __forceinline__ void gemm_phase(PG8_LAS unsigned char* lds, const Gemm g, const Sched& S, const Epi& E) {
;     ...
;         const bool has_next = S.next(ui + 1, nxt);
;         const char* nA = has_next ? (const char*)g.A + (size_t)nxt.pm * tstep : cA; const char* nB = has_next ? (const char*)g.Bt + (size_t)nxt.pn * tstep : cB;
;         for (int t = 0; t < nt; t += 2) {
;             const bool last = (t == nt - 2);
;             const char* a1 = cA + (size_t)(t + 1) * kstep;
;             const char* a2 = last ? nA : cA + (size_t)(t + 2) * kstep; const char* b2 = last ? nB : cB + (size_t)(t + 2) * kstep;
;             const char* a3 = a2 + kstep; const char* b3 = b2 + kstep;
;             if (last && has_next) S.a_ready(nxt);
;             if constexpr (SP2) {
;             PG8_LDB(B0, 0, 0); PG8_LDB(B1, 0, 1); PG8_SCHED; PG8_LDA(At, 0, 0); PG8_STAGE(PG8_SA(1, 1), a1 + hstep, voffA);
;             PG8_WAIT_V(8); PG8_WAIT_L(0); PG8_BAR; PG8_MMA(0, 0, At, B0); PG8_MMA(0, 1, At, B1); PG8_BAR; PG8_SCHED;
;             PG8_LDA(At, 0, 1); PG8_STAGE(PG8_SB(0, 0), b2, voffB); PG8_STAGE(PG8_SB(0, 1), b2 + hstep, voffB); PG8_STAGE(PG8_SA(0, 0), a2, voffA);
;             PG8_WAIT_V(8); PG8_WAIT_L(0); PG8_BAR; PG8_MMA(1, 0, At, B0); PG8_MMA(1, 1, At, B1); PG8_BAR; PG8_SCHED;
.LBB0_1121:
	s_ashr_i32 s43, s42, 31
	s_lshl_b64 s[28:29], s[42:43], 19
	v_readlane_b32 s19, v253, 59
	s_add_u32 s44, s19, s28
	v_readlane_b32 s19, v253, 60
	s_addc_u32 s45, s19, s29
	s_and_b64 s[28:29], s[38:39], exec
	s_cselect_b32 s19, s45, s11
	s_cselect_b32 s23, s44, s10
	s_ashr_i32 s41, s40, 31
	s_lshl_b64 s[28:29], s[40:41], 19
	s_add_u32 s46, s22, s28
	s_addc_u32 s47, s50, s29
	s_and_b64 s[28:29], s[38:39], exec
	s_cselect_b32 s28, s47, s37
	s_cselect_b32 s29, s46, s36
	s_add_u32 s10, s10, 0x40080
	s_addc_u32 s11, s11, 0
	s_add_u32 s34, s36, 0x100
	s_addc_u32 s35, s37, 0
	s_mov_b32 s41, -2
	s_add_u32 s36, s10, 0xfffc0080
	s_addc_u32 s37, s11, -1
	s_add_i32 s43, 0, 0x10000
	s_cmp_eq_u32 s41, 12
	s_cselect_b32 s49, s19, s37
	s_cselect_b32 s48, s23, s36
	s_cselect_b32 s37, s28, s35
	s_cselect_b32 s36, s29, s34
	s_add_i32 s56, 0, 0x14000
	v_add_u32_e32 v0, s43, v213
	v_add_u32_e32 v12, s56, v213
	ds_read_b128 v[16:19], v0
	ds_read_b128 v[20:23], v0 offset:1024
	ds_read_b128 v[24:27], v0 offset:2048
	ds_read_b128 v[28:31], v0 offset:3072
	ds_read_b128 v[0:3], v12
	ds_read_b128 v[4:7], v12 offset:1024
	ds_read_b128 v[8:11], v12 offset:2048
	ds_read_b128 v[12:15], v12 offset:3072
	v_lshl_add_u64 v[162:163], s[10:11], 0, v[190:191]
	s_add_i32 m0, s51, 0xc000
	ds_read_b128 v[194:197], v215
	ds_read_b128 v[198:201], v215 offset:1024
	ds_read_b128 v[216:219], v215 offset:2048
	ds_read_b128 v[220:223], v215 offset:3072
	ds_read_b128 v[224:227], v215 offset:4096
	ds_read_b128 v[228:231], v215 offset:5120
	ds_read_b128 v[232:235], v215 offset:6144
	ds_read_b128 v[236:239], v215 offset:7168
	global_load_lds_dwordx4 v[162:163], off
	v_lshl_add_u64 v[162:163], s[10:11], 0, v[192:193]
	s_add_i32 m0, s51, 0xe000
	s_nop 0
	global_load_lds_dwordx4 v[162:163], off
	s_waitcnt vmcnt(8)
	s_waitcnt lgkmcnt(0)
	s_barrier
	s_setprio 1
	s_waitcnt lgkmcnt(0)
	v_mfma_f32_16x16x128_f8f6f4 v[156:159], v[16:23], v[194:201], 0
	v_mfma_f32_16x16x128_f8f6f4 v[152:155], v[24:31], v[194:201], 0
	v_mfma_f32_16x16x128_f8f6f4 v[140:143], v[16:23], v[216:223], 0
	v_mfma_f32_16x16x128_f8f6f4 v[136:139], v[24:31], v[216:223], 0
	v_mfma_f32_16x16x128_f8f6f4 v[124:127], v[16:23], v[224:231], 0
	v_mfma_f32_16x16x128_f8f6f4 v[120:123], v[24:31], v[224:231], 0
	v_mfma_f32_16x16x128_f8f6f4 v[108:111], v[16:23], v[232:239], 0
	v_mfma_f32_16x16x128_f8f6f4 v[104:107], v[24:31], v[232:239], 0
	s_setprio 0
	s_setprio 1
	v_mfma_f32_16x16x128_f8f6f4 v[148:151], v[0:7], v[194:201], 0
	v_mfma_f32_16x16x128_f8f6f4 v[144:147], v[8:15], v[194:201], 0
	v_mfma_f32_16x16x128_f8f6f4 v[132:135], v[0:7], v[216:223], 0
	v_mfma_f32_16x16x128_f8f6f4 v[128:131], v[8:15], v[216:223], 0
	v_mfma_f32_16x16x128_f8f6f4 v[116:119], v[0:7], v[224:231], 0
	v_mfma_f32_16x16x128_f8f6f4 v[112:115], v[8:15], v[224:231], 0
	v_mfma_f32_16x16x128_f8f6f4 v[100:103], v[0:7], v[232:239], 0
	v_mfma_f32_16x16x128_f8f6f4 v[96:99], v[8:15], v[232:239], 0
	s_setprio 0
	s_barrier
	s_add_i32 s43, s43, s13
	v_lshl_add_u64 v[194:195], s[36:37], 0, v[160:161]
	s_mov_b32 m0, s43
	ds_read_b128 v[216:219], v215 offset:16384
	ds_read_b128 v[220:223], v215 offset:17408
	ds_read_b128 v[224:227], v215 offset:18432
	ds_read_b128 v[228:231], v215 offset:19456
	ds_read_b128 v[232:235], v215 offset:20480
	ds_read_b128 v[236:239], v215 offset:21504
	ds_read_b128 v[240:243], v215 offset:22528
	ds_read_b128 v[244:247], v215 offset:23552
	global_load_lds_dwordx4 v[194:195], off
	s_add_i32 m0, s43, 0x2000
	s_add_u32 s60, s36, 0x40000
	v_lshl_add_u64 v[196:197], s[36:37], 0, v[184:185]
	s_addc_u32 s61, s37, 0
	s_add_i32 s43, s56, s13
	global_load_lds_dwordx4 v[196:197], off
	v_lshl_add_u64 v[162:163], s[60:61], 0, v[160:161]
	s_mov_b32 m0, s43
	v_lshl_add_u64 v[198:199], s[48:49], 0, v[188:189]
	global_load_lds_dwordx4 v[162:163], off
	v_lshl_add_u64 v[162:163], s[60:61], 0, v[184:185]
	s_add_i32 m0, s43, 0x2000
	v_lshl_add_u64 v[200:201], s[48:49], 0, v[186:187]
	global_load_lds_dwordx4 v[162:163], off
	s_mov_b32 m0, s51
	s_nop 0
	global_load_lds_dwordx4 v[198:199], off
	s_mov_b32 m0, s52
	s_nop 0
	global_load_lds_dwordx4 v[200:201], off
	s_waitcnt vmcnt(8)
	s_waitcnt lgkmcnt(0)
	s_barrier
	s_setprio 1
	s_waitcnt lgkmcnt(0)
	v_mfma_f32_16x16x128_f8f6f4 v[92:95], v[16:23], v[216:223], 0
	v_mfma_f32_16x16x128_f8f6f4 v[88:91], v[24:31], v[216:223], 0
	v_mfma_f32_16x16x128_f8f6f4 v[76:79], v[16:23], v[224:231], 0
	v_mfma_f32_16x16x128_f8f6f4 v[72:75], v[24:31], v[224:231], 0
	v_mfma_f32_16x16x128_f8f6f4 v[60:63], v[16:23], v[232:239], 0
	v_mfma_f32_16x16x128_f8f6f4 v[56:59], v[24:31], v[232:239], 0
	v_mfma_f32_16x16x128_f8f6f4 v[44:47], v[16:23], v[240:247], 0
	v_mfma_f32_16x16x128_f8f6f4 v[40:43], v[24:31], v[240:247], 0
	s_setprio 0
	s_setprio 1
	v_mfma_f32_16x16x128_f8f6f4 v[84:87], v[0:7], v[216:223], 0
	v_mfma_f32_16x16x128_f8f6f4 v[80:83], v[8:15], v[216:223], 0
	v_mfma_f32_16x16x128_f8f6f4 v[68:71], v[0:7], v[224:231], 0
	v_mfma_f32_16x16x128_f8f6f4 v[64:67], v[8:15], v[224:231], 0
	v_mfma_f32_16x16x128_f8f6f4 v[52:55], v[0:7], v[232:239], 0
	v_mfma_f32_16x16x128_f8f6f4 v[48:51], v[8:15], v[232:239], 0
	v_mfma_f32_16x16x128_f8f6f4 v[36:39], v[0:7], v[240:247], 0
	v_mfma_f32_16x16x128_f8f6f4 v[32:35], v[8:15], v[240:247], 0
	s_setprio 0
	s_barrier
; #define PG8_STAGE(bufoff, gbase, voff) do { _Pragma("unroll") for (int _i = 0; _i < 2; ++_i) \
;         __builtin_amdgcn_global_load_lds((const unsigned*)((const char*)(gbase) + (voff)[_i]), (PG8_LAS unsigned*)(lds + (bufoff) + ldsw + _i * 8192), 16, 0, 0); } while (0)
; #define PG8_WAIT_V(n) asm volatile("s_waitcnt vmcnt(" #n ")" ::: "memory")
; #define PG8_WAIT_L(n) asm volatile("s_waitcnt lgkmcnt(" #n ")" ::: "memory")
; #define PG8_BAR __builtin_amdgcn_s_barrier()
; #define PG8_SCHED __builtin_amdgcn_sched_barrier(0)
; template <class Epi, class Sched, bool ALIGN_EPI = false, bool SP2 = false, bool F8 = false>
; __device__ __forceinline__ void gemm_phase(PG8_LAS unsigned char* lds, const Gemm g, const Sched& S, const Epi& E) {
;     ...
;             PG8_LDB(B0, 1, 0); PG8_LDB(B1, 1, 1); PG8_SCHED; PG8_LDA(At, 1, 0); PG8_STAGE(PG8_SA(0, 1), a2 + hstep, voffA);
;             PG8_WAIT_V(8); PG8_WAIT_L(0); PG8_BAR; PG8_MMA(0, 0, At, B0); PG8_MMA(0, 1, At, B1); PG8_BAR; PG8_SCHED;
;             PG8_LDA(At, 1, 1); PG8_STAGE(PG8_SB(1, 0), b3, voffB); PG8_STAGE(PG8_SB(1, 1), b3 + hstep, voffB); PG8_STAGE(PG8_SA(1, 0), a3, voffA);
;             PG8_WAIT_V(8); PG8_WAIT_L(0); PG8_BAR; PG8_MMA(1, 0, At, B0); PG8_MMA(1, 1, At, B1); PG8_BAR; PG8_SCHED;
	s_add_i32 s43, 0, 0x18000
	s_add_i32 s56, 0, 0x1c000
	v_add_u32_e32 v12, s43, v213
	v_add_u32_e32 v28, s56, v213
	ds_read_b128 v[0:3], v12
	ds_read_b128 v[4:7], v12 offset:1024
	ds_read_b128 v[8:11], v12 offset:2048
	ds_read_b128 v[12:15], v12 offset:3072
	ds_read_b128 v[16:19], v28
	ds_read_b128 v[20:23], v28 offset:1024
	ds_read_b128 v[24:27], v28 offset:2048
	ds_read_b128 v[28:31], v28 offset:3072
	s_add_u32 s48, s48, 0x40000
	s_addc_u32 s49, s49, 0
	s_mov_b32 m0, s53
	v_lshl_add_u64 v[162:163], s[48:49], 0, v[188:189]
	ds_read_b128 v[216:219], v215 offset:32768
	ds_read_b128 v[220:223], v215 offset:33792
	ds_read_b128 v[224:227], v215 offset:34816
	ds_read_b128 v[228:231], v215 offset:35840
	ds_read_b128 v[232:235], v215 offset:36864
	ds_read_b128 v[236:239], v215 offset:37888
	ds_read_b128 v[240:243], v215 offset:38912
	ds_read_b128 v[244:247], v215 offset:39936
	global_load_lds_dwordx4 v[162:163], off
	v_lshl_add_u64 v[162:163], s[48:49], 0, v[186:187]
	s_mov_b32 m0, s54
	s_nop 0
	global_load_lds_dwordx4 v[162:163], off
	s_waitcnt vmcnt(8)
	s_waitcnt lgkmcnt(0)
	s_barrier
	s_setprio 1
	s_waitcnt lgkmcnt(0)
	v_mfma_f32_16x16x128_f8f6f4 v[156:159], v[0:7], v[216:223], v[156:159]
	v_mfma_f32_16x16x128_f8f6f4 v[152:155], v[8:15], v[216:223], v[152:155]
	v_mfma_f32_16x16x128_f8f6f4 v[140:143], v[0:7], v[224:231], v[140:143]
	v_mfma_f32_16x16x128_f8f6f4 v[136:139], v[8:15], v[224:231], v[136:139]
	v_mfma_f32_16x16x128_f8f6f4 v[124:127], v[0:7], v[232:239], v[124:127]
	v_mfma_f32_16x16x128_f8f6f4 v[120:123], v[8:15], v[232:239], v[120:123]
	v_mfma_f32_16x16x128_f8f6f4 v[108:111], v[0:7], v[240:247], v[108:111]
	v_mfma_f32_16x16x128_f8f6f4 v[104:107], v[8:15], v[240:247], v[104:107]
	s_setprio 0
	s_setprio 1
	v_mfma_f32_16x16x128_f8f6f4 v[148:151], v[16:23], v[216:223], v[148:151]
	v_mfma_f32_16x16x128_f8f6f4 v[144:147], v[24:31], v[216:223], v[144:147]
	v_mfma_f32_16x16x128_f8f6f4 v[132:135], v[16:23], v[224:231], v[132:135]
	v_mfma_f32_16x16x128_f8f6f4 v[128:131], v[24:31], v[224:231], v[128:131]
	v_mfma_f32_16x16x128_f8f6f4 v[116:119], v[16:23], v[232:239], v[116:119]
	v_mfma_f32_16x16x128_f8f6f4 v[112:115], v[24:31], v[232:239], v[112:115]
	v_mfma_f32_16x16x128_f8f6f4 v[100:103], v[16:23], v[240:247], v[100:103]
	v_mfma_f32_16x16x128_f8f6f4 v[96:99], v[24:31], v[240:247], v[96:99]
	s_setprio 0
	s_barrier
	s_add_i32 s43, s43, s13
	v_lshl_add_u64 v[162:163], v[194:195], 0, s[14:15]
	s_mov_b32 m0, s43
	ds_read_b128 v[216:219], v215 offset:49152
	ds_read_b128 v[220:223], v215 offset:50176
	ds_read_b128 v[224:227], v215 offset:51200
	ds_read_b128 v[228:231], v215 offset:52224
	ds_read_b128 v[232:235], v215 offset:53248
	ds_read_b128 v[236:239], v215 offset:54272
	ds_read_b128 v[240:243], v215 offset:55296
	ds_read_b128 v[244:247], v215 offset:56320
	global_load_lds_dwordx4 v[162:163], off
	s_add_i32 m0, s43, 0x2000
	s_add_u32 s36, s36, 0x40080
	v_lshl_add_u64 v[162:163], v[196:197], 0, s[14:15]
	s_addc_u32 s37, s37, 0
	s_add_i32 s43, s56, s13
	global_load_lds_dwordx4 v[162:163], off
	v_lshl_add_u64 v[162:163], s[36:37], 0, v[160:161]
	s_mov_b32 m0, s43
	s_nop 0
	global_load_lds_dwordx4 v[162:163], off
	v_lshl_add_u64 v[162:163], s[36:37], 0, v[184:185]
	s_add_i32 m0, s43, 0x2000
	s_nop 0
	global_load_lds_dwordx4 v[162:163], off
	v_lshl_add_u64 v[162:163], v[198:199], 0, s[14:15]
	s_mov_b32 m0, s55
	s_nop 0
	global_load_lds_dwordx4 v[162:163], off
	v_lshl_add_u64 v[162:163], v[200:201], 0, s[14:15]
	s_mov_b32 m0, s58
	s_nop 0
	global_load_lds_dwordx4 v[162:163], off
	s_waitcnt vmcnt(8)
	s_waitcnt lgkmcnt(0)
	s_barrier
	s_setprio 1
	s_waitcnt lgkmcnt(0)
	v_mfma_f32_16x16x128_f8f6f4 v[92:95], v[0:7], v[216:223], v[92:95]
	v_mfma_f32_16x16x128_f8f6f4 v[88:91], v[8:15], v[216:223], v[88:91]
	v_mfma_f32_16x16x128_f8f6f4 v[76:79], v[0:7], v[224:231], v[76:79]
	v_mfma_f32_16x16x128_f8f6f4 v[72:75], v[8:15], v[224:231], v[72:75]
	v_mfma_f32_16x16x128_f8f6f4 v[60:63], v[0:7], v[232:239], v[60:63]
	v_mfma_f32_16x16x128_f8f6f4 v[56:59], v[8:15], v[232:239], v[56:59]
	v_mfma_f32_16x16x128_f8f6f4 v[44:47], v[0:7], v[240:247], v[44:47]
	v_mfma_f32_16x16x128_f8f6f4 v[40:43], v[8:15], v[240:247], v[40:43]
	s_setprio 0
	s_setprio 1
	v_mfma_f32_16x16x128_f8f6f4 v[84:87], v[16:23], v[216:223], v[84:87]
	v_mfma_f32_16x16x128_f8f6f4 v[80:83], v[24:31], v[216:223], v[80:83]
	v_mfma_f32_16x16x128_f8f6f4 v[68:71], v[16:23], v[224:231], v[68:71]
	v_mfma_f32_16x16x128_f8f6f4 v[64:67], v[24:31], v[224:231], v[64:67]
	v_mfma_f32_16x16x128_f8f6f4 v[52:55], v[16:23], v[232:239], v[52:55]
	v_mfma_f32_16x16x128_f8f6f4 v[48:51], v[24:31], v[232:239], v[48:51]
	v_mfma_f32_16x16x128_f8f6f4 v[36:39], v[16:23], v[240:247], v[36:39]
	v_mfma_f32_16x16x128_f8f6f4 v[32:35], v[24:31], v[240:247], v[32:35]
	s_setprio 0
	s_barrier
	s_add_i32 s41, s41, 2
	s_add_u32 s10, s10, 0x100
	s_addc_u32 s11, s11, 0
	s_add_u32 s34, s34, 0x100
	s_addc_u32 s35, s35, 0
	s_cmp_gt_u32 s41, 13
	s_cbranch_scc0 .LBB0_1122
	s_branch .Lgk_after_1122
; #define PG8_STAGE(bufoff, gbase, voff) do { _Pragma("unroll") for (int _i = 0; _i < 2; ++_i) \
;         __builtin_amdgcn_global_load_lds((const unsigned*)((const char*)(gbase) + (voff)[_i]), (PG8_LAS unsigned*)(lds + (bufoff) + ldsw + _i * 8192), 16, 0, 0); } while (0)
; #define PG8_WAIT_V(n) asm volatile("s_waitcnt vmcnt(" #n ")" ::: "memory")
; #define PG8_WAIT_L(n) asm volatile("s_waitcnt lgkmcnt(" #n ")" ::: "memory")
; #define PG8_BAR __builtin_amdgcn_s_barrier()
; #define PG8_SCHED __builtin_amdgcn_sched_barrier(0)
; template <class Epi, class Sched, bool ALIGN_EPI = false, bool SP2 = false, bool F8 = false>
; __device__ __forceinline__ void gemm_phase(PG8_LAS unsigned char* lds, const Gemm g, const Sched& S, const Epi& E) {
;     ...
;             const bool last = (t == nt - 2);
;             const char* a1 = cA + (size_t)(t + 1) * kstep;
;             const char* a2 = last ? nA : cA + (size_t)(t + 2) * kstep; const char* b2 = last ? nB : cB + (size_t)(t + 2) * kstep;
;             const char* a3 = a2 + kstep; const char* b3 = b2 + kstep;
;             if (last && has_next) S.a_ready(nxt);
;             if constexpr (SP2) {
;             PG8_LDB(B0, 0, 0); PG8_LDB(B1, 0, 1); PG8_SCHED; PG8_LDA(At, 0, 0); PG8_STAGE(PG8_SA(1, 1), a1 + hstep, voffA);
;             PG8_WAIT_V(8); PG8_WAIT_L(0); PG8_BAR; PG8_MMA(0, 0, At, B0); PG8_MMA(0, 1, At, B1); PG8_BAR; PG8_SCHED;
;             PG8_LDA(At, 0, 1); PG8_STAGE(PG8_SB(0, 0), b2, voffB); PG8_STAGE(PG8_SB(0, 1), b2 + hstep, voffB); PG8_STAGE(PG8_SA(0, 0), a2, voffA);
;             PG8_WAIT_V(8); PG8_WAIT_L(0); PG8_BAR; PG8_MMA(1, 0, At, B0); PG8_MMA(1, 1, At, B1); PG8_BAR; PG8_SCHED;
.LBB0_1122:
	s_add_u32 s36, s10, 0xfffc0080
	s_addc_u32 s37, s11, -1
	s_add_i32 s43, 0, 0x10000
	s_cmp_eq_u32 s41, 12
	s_cselect_b32 s49, s19, s37
	s_cselect_b32 s48, s23, s36
	s_cselect_b32 s37, s28, s35
	s_cselect_b32 s36, s29, s34
	s_add_i32 s56, 0, 0x14000
	v_add_u32_e32 v0, s43, v213
	v_add_u32_e32 v12, s56, v213
	ds_read_b128 v[16:19], v0
	ds_read_b128 v[20:23], v0 offset:1024
	ds_read_b128 v[24:27], v0 offset:2048
	ds_read_b128 v[28:31], v0 offset:3072
	ds_read_b128 v[0:3], v12
	ds_read_b128 v[4:7], v12 offset:1024
	ds_read_b128 v[8:11], v12 offset:2048
	ds_read_b128 v[12:15], v12 offset:3072
	v_lshl_add_u64 v[162:163], s[10:11], 0, v[190:191]
	s_add_i32 m0, s51, 0xc000
	ds_read_b128 v[194:197], v215
	ds_read_b128 v[198:201], v215 offset:1024
	ds_read_b128 v[216:219], v215 offset:2048
	ds_read_b128 v[220:223], v215 offset:3072
	ds_read_b128 v[224:227], v215 offset:4096
	ds_read_b128 v[228:231], v215 offset:5120
	ds_read_b128 v[232:235], v215 offset:6144
	ds_read_b128 v[236:239], v215 offset:7168
	global_load_lds_dwordx4 v[162:163], off
	v_lshl_add_u64 v[162:163], s[10:11], 0, v[192:193]
	s_add_i32 m0, s51, 0xe000
	s_nop 0
	global_load_lds_dwordx4 v[162:163], off
	s_waitcnt vmcnt(8)
	s_waitcnt lgkmcnt(0)
	s_barrier
	s_setprio 1
	s_waitcnt lgkmcnt(0)
	v_mfma_f32_16x16x128_f8f6f4 v[156:159], v[16:23], v[194:201], v[156:159]
	v_mfma_f32_16x16x128_f8f6f4 v[152:155], v[24:31], v[194:201], v[152:155]
	v_mfma_f32_16x16x128_f8f6f4 v[140:143], v[16:23], v[216:223], v[140:143]
	v_mfma_f32_16x16x128_f8f6f4 v[136:139], v[24:31], v[216:223], v[136:139]
	v_mfma_f32_16x16x128_f8f6f4 v[124:127], v[16:23], v[224:231], v[124:127]
	v_mfma_f32_16x16x128_f8f6f4 v[120:123], v[24:31], v[224:231], v[120:123]
	v_mfma_f32_16x16x128_f8f6f4 v[108:111], v[16:23], v[232:239], v[108:111]
	v_mfma_f32_16x16x128_f8f6f4 v[104:107], v[24:31], v[232:239], v[104:107]
	s_setprio 0
	s_setprio 1
	v_mfma_f32_16x16x128_f8f6f4 v[148:151], v[0:7], v[194:201], v[148:151]
	v_mfma_f32_16x16x128_f8f6f4 v[144:147], v[8:15], v[194:201], v[144:147]
	v_mfma_f32_16x16x128_f8f6f4 v[132:135], v[0:7], v[216:223], v[132:135]
	v_mfma_f32_16x16x128_f8f6f4 v[128:131], v[8:15], v[216:223], v[128:131]
	v_mfma_f32_16x16x128_f8f6f4 v[116:119], v[0:7], v[224:231], v[116:119]
	v_mfma_f32_16x16x128_f8f6f4 v[112:115], v[8:15], v[224:231], v[112:115]
	v_mfma_f32_16x16x128_f8f6f4 v[100:103], v[0:7], v[232:239], v[100:103]
	v_mfma_f32_16x16x128_f8f6f4 v[96:99], v[8:15], v[232:239], v[96:99]
	s_setprio 0
	s_barrier
	s_add_i32 s43, s43, s13
	v_lshl_add_u64 v[194:195], s[36:37], 0, v[160:161]
	s_mov_b32 m0, s43
	ds_read_b128 v[216:219], v215 offset:16384
	ds_read_b128 v[220:223], v215 offset:17408
	ds_read_b128 v[224:227], v215 offset:18432
	ds_read_b128 v[228:231], v215 offset:19456
	ds_read_b128 v[232:235], v215 offset:20480
	ds_read_b128 v[236:239], v215 offset:21504
	ds_read_b128 v[240:243], v215 offset:22528
	ds_read_b128 v[244:247], v215 offset:23552
	global_load_lds_dwordx4 v[194:195], off
	s_add_i32 m0, s43, 0x2000
	s_add_u32 s60, s36, 0x40000
	v_lshl_add_u64 v[196:197], s[36:37], 0, v[184:185]
	s_addc_u32 s61, s37, 0
	s_add_i32 s43, s56, s13
	global_load_lds_dwordx4 v[196:197], off
	v_lshl_add_u64 v[162:163], s[60:61], 0, v[160:161]
	s_mov_b32 m0, s43
	v_lshl_add_u64 v[198:199], s[48:49], 0, v[188:189]
	global_load_lds_dwordx4 v[162:163], off
	v_lshl_add_u64 v[162:163], s[60:61], 0, v[184:185]
	s_add_i32 m0, s43, 0x2000
	v_lshl_add_u64 v[200:201], s[48:49], 0, v[186:187]
	global_load_lds_dwordx4 v[162:163], off
	s_mov_b32 m0, s51
	s_nop 0
	global_load_lds_dwordx4 v[198:199], off
	s_mov_b32 m0, s52
	s_nop 0
	global_load_lds_dwordx4 v[200:201], off
	s_waitcnt vmcnt(8)
	s_waitcnt lgkmcnt(0)
	s_barrier
	s_setprio 1
	s_waitcnt lgkmcnt(0)
	v_mfma_f32_16x16x128_f8f6f4 v[92:95], v[16:23], v[216:223], v[92:95]
	v_mfma_f32_16x16x128_f8f6f4 v[88:91], v[24:31], v[216:223], v[88:91]
	v_mfma_f32_16x16x128_f8f6f4 v[76:79], v[16:23], v[224:231], v[76:79]
	v_mfma_f32_16x16x128_f8f6f4 v[72:75], v[24:31], v[224:231], v[72:75]
	v_mfma_f32_16x16x128_f8f6f4 v[60:63], v[16:23], v[232:239], v[60:63]
	v_mfma_f32_16x16x128_f8f6f4 v[56:59], v[24:31], v[232:239], v[56:59]
	v_mfma_f32_16x16x128_f8f6f4 v[44:47], v[16:23], v[240:247], v[44:47]
	v_mfma_f32_16x16x128_f8f6f4 v[40:43], v[24:31], v[240:247], v[40:43]
	s_setprio 0
	s_setprio 1
	v_mfma_f32_16x16x128_f8f6f4 v[84:87], v[0:7], v[216:223], v[84:87]
	v_mfma_f32_16x16x128_f8f6f4 v[80:83], v[8:15], v[216:223], v[80:83]
	v_mfma_f32_16x16x128_f8f6f4 v[68:71], v[0:7], v[224:231], v[68:71]
	v_mfma_f32_16x16x128_f8f6f4 v[64:67], v[8:15], v[224:231], v[64:67]
	v_mfma_f32_16x16x128_f8f6f4 v[52:55], v[0:7], v[232:239], v[52:55]
	v_mfma_f32_16x16x128_f8f6f4 v[48:51], v[8:15], v[232:239], v[48:51]
	v_mfma_f32_16x16x128_f8f6f4 v[36:39], v[0:7], v[240:247], v[36:39]
	v_mfma_f32_16x16x128_f8f6f4 v[32:35], v[8:15], v[240:247], v[32:35]
	s_setprio 0
	s_barrier
; #define PG8_STAGE(bufoff, gbase, voff) do { _Pragma("unroll") for (int _i = 0; _i < 2; ++_i) \
;         __builtin_amdgcn_global_load_lds((const unsigned*)((const char*)(gbase) + (voff)[_i]), (PG8_LAS unsigned*)(lds + (bufoff) + ldsw + _i * 8192), 16, 0, 0); } while (0)
; #define PG8_WAIT_V(n) asm volatile("s_waitcnt vmcnt(" #n ")" ::: "memory")
; #define PG8_WAIT_L(n) asm volatile("s_waitcnt lgkmcnt(" #n ")" ::: "memory")
; #define PG8_BAR __builtin_amdgcn_s_barrier()
; #define PG8_SCHED __builtin_amdgcn_sched_barrier(0)
; template <class Epi, class Sched, bool ALIGN_EPI = false, bool SP2 = false, bool F8 = false>
; __device__ __forceinline__ void gemm_phase(PG8_LAS unsigned char* lds, const Gemm g, const Sched& S, const Epi& E) {
;     ...
;             PG8_LDB(B0, 1, 0); PG8_LDB(B1, 1, 1); PG8_SCHED; PG8_LDA(At, 1, 0); PG8_STAGE(PG8_SA(0, 1), a2 + hstep, voffA);
;             PG8_WAIT_V(8); PG8_WAIT_L(0); PG8_BAR; PG8_MMA(0, 0, At, B0); PG8_MMA(0, 1, At, B1); PG8_BAR; PG8_SCHED;
;             PG8_LDA(At, 1, 1); PG8_STAGE(PG8_SB(1, 0), b3, voffB); PG8_STAGE(PG8_SB(1, 1), b3 + hstep, voffB); PG8_STAGE(PG8_SA(1, 0), a3, voffA);
;             PG8_WAIT_V(8); PG8_WAIT_L(0); PG8_BAR; PG8_MMA(1, 0, At, B0); PG8_MMA(1, 1, At, B1); PG8_BAR; PG8_SCHED;
	s_add_i32 s43, 0, 0x18000
	s_add_i32 s56, 0, 0x1c000
	v_add_u32_e32 v12, s43, v213
	v_add_u32_e32 v28, s56, v213
	ds_read_b128 v[0:3], v12
	ds_read_b128 v[4:7], v12 offset:1024
	ds_read_b128 v[8:11], v12 offset:2048
	ds_read_b128 v[12:15], v12 offset:3072
	ds_read_b128 v[16:19], v28
	ds_read_b128 v[20:23], v28 offset:1024
	ds_read_b128 v[24:27], v28 offset:2048
	ds_read_b128 v[28:31], v28 offset:3072
	s_add_u32 s48, s48, 0x40000
	s_addc_u32 s49, s49, 0
	s_mov_b32 m0, s53
	v_lshl_add_u64 v[162:163], s[48:49], 0, v[188:189]
	ds_read_b128 v[216:219], v215 offset:32768
	ds_read_b128 v[220:223], v215 offset:33792
	ds_read_b128 v[224:227], v215 offset:34816
	ds_read_b128 v[228:231], v215 offset:35840
	ds_read_b128 v[232:235], v215 offset:36864
	ds_read_b128 v[236:239], v215 offset:37888
	ds_read_b128 v[240:243], v215 offset:38912
	ds_read_b128 v[244:247], v215 offset:39936
	global_load_lds_dwordx4 v[162:163], off
	v_lshl_add_u64 v[162:163], s[48:49], 0, v[186:187]
	s_mov_b32 m0, s54
	s_nop 0
	global_load_lds_dwordx4 v[162:163], off
	s_waitcnt vmcnt(8)
	s_waitcnt lgkmcnt(0)
	s_barrier
	s_setprio 1
	s_waitcnt lgkmcnt(0)
	v_mfma_f32_16x16x128_f8f6f4 v[156:159], v[0:7], v[216:223], v[156:159]
	v_mfma_f32_16x16x128_f8f6f4 v[152:155], v[8:15], v[216:223], v[152:155]
	v_mfma_f32_16x16x128_f8f6f4 v[140:143], v[0:7], v[224:231], v[140:143]
	v_mfma_f32_16x16x128_f8f6f4 v[136:139], v[8:15], v[224:231], v[136:139]
	v_mfma_f32_16x16x128_f8f6f4 v[124:127], v[0:7], v[232:239], v[124:127]
	v_mfma_f32_16x16x128_f8f6f4 v[120:123], v[8:15], v[232:239], v[120:123]
	v_mfma_f32_16x16x128_f8f6f4 v[108:111], v[0:7], v[240:247], v[108:111]
	v_mfma_f32_16x16x128_f8f6f4 v[104:107], v[8:15], v[240:247], v[104:107]
	s_setprio 0
	s_setprio 1
	v_mfma_f32_16x16x128_f8f6f4 v[148:151], v[16:23], v[216:223], v[148:151]
	v_mfma_f32_16x16x128_f8f6f4 v[144:147], v[24:31], v[216:223], v[144:147]
	v_mfma_f32_16x16x128_f8f6f4 v[132:135], v[16:23], v[224:231], v[132:135]
	v_mfma_f32_16x16x128_f8f6f4 v[128:131], v[24:31], v[224:231], v[128:131]
	v_mfma_f32_16x16x128_f8f6f4 v[116:119], v[16:23], v[232:239], v[116:119]
	v_mfma_f32_16x16x128_f8f6f4 v[112:115], v[24:31], v[232:239], v[112:115]
	v_mfma_f32_16x16x128_f8f6f4 v[100:103], v[16:23], v[240:247], v[100:103]
	v_mfma_f32_16x16x128_f8f6f4 v[96:99], v[24:31], v[240:247], v[96:99]
	s_setprio 0
	s_barrier
	s_add_i32 s43, s43, s13
	v_lshl_add_u64 v[162:163], v[194:195], 0, s[14:15]
	s_mov_b32 m0, s43
	ds_read_b128 v[216:219], v215 offset:49152
	ds_read_b128 v[220:223], v215 offset:50176
	ds_read_b128 v[224:227], v215 offset:51200
	ds_read_b128 v[228:231], v215 offset:52224
	ds_read_b128 v[232:235], v215 offset:53248
	ds_read_b128 v[236:239], v215 offset:54272
	ds_read_b128 v[240:243], v215 offset:55296
	ds_read_b128 v[244:247], v215 offset:56320
	global_load_lds_dwordx4 v[162:163], off
	s_add_i32 m0, s43, 0x2000
	s_add_u32 s36, s36, 0x40080
	v_lshl_add_u64 v[162:163], v[196:197], 0, s[14:15]
	s_addc_u32 s37, s37, 0
	s_add_i32 s43, s56, s13
	global_load_lds_dwordx4 v[162:163], off
	v_lshl_add_u64 v[162:163], s[36:37], 0, v[160:161]
	s_mov_b32 m0, s43
	s_nop 0
	global_load_lds_dwordx4 v[162:163], off
	v_lshl_add_u64 v[162:163], s[36:37], 0, v[184:185]
	s_add_i32 m0, s43, 0x2000
	s_nop 0
	global_load_lds_dwordx4 v[162:163], off
	v_lshl_add_u64 v[162:163], v[198:199], 0, s[14:15]
	s_mov_b32 m0, s55
	s_nop 0
	global_load_lds_dwordx4 v[162:163], off
	v_lshl_add_u64 v[162:163], v[200:201], 0, s[14:15]
	s_mov_b32 m0, s58
	s_nop 0
	global_load_lds_dwordx4 v[162:163], off
	s_waitcnt vmcnt(8)
	s_waitcnt lgkmcnt(0)
	s_barrier
	s_setprio 1
	s_waitcnt lgkmcnt(0)
	v_mfma_f32_16x16x128_f8f6f4 v[92:95], v[0:7], v[216:223], v[92:95]
	v_mfma_f32_16x16x128_f8f6f4 v[88:91], v[8:15], v[216:223], v[88:91]
	v_mfma_f32_16x16x128_f8f6f4 v[76:79], v[0:7], v[224:231], v[76:79]
	v_mfma_f32_16x16x128_f8f6f4 v[72:75], v[8:15], v[224:231], v[72:75]
	v_mfma_f32_16x16x128_f8f6f4 v[60:63], v[0:7], v[232:239], v[60:63]
	v_mfma_f32_16x16x128_f8f6f4 v[56:59], v[8:15], v[232:239], v[56:59]
	v_mfma_f32_16x16x128_f8f6f4 v[44:47], v[0:7], v[240:247], v[44:47]
	v_mfma_f32_16x16x128_f8f6f4 v[40:43], v[8:15], v[240:247], v[40:43]
	s_setprio 0
	s_setprio 1
	v_mfma_f32_16x16x128_f8f6f4 v[84:87], v[16:23], v[216:223], v[84:87]
	v_mfma_f32_16x16x128_f8f6f4 v[80:83], v[24:31], v[216:223], v[80:83]
	v_mfma_f32_16x16x128_f8f6f4 v[68:71], v[16:23], v[224:231], v[68:71]
	v_mfma_f32_16x16x128_f8f6f4 v[64:67], v[24:31], v[224:231], v[64:67]
	v_mfma_f32_16x16x128_f8f6f4 v[52:55], v[16:23], v[232:239], v[52:55]
	v_mfma_f32_16x16x128_f8f6f4 v[48:51], v[24:31], v[232:239], v[48:51]
	v_mfma_f32_16x16x128_f8f6f4 v[36:39], v[16:23], v[240:247], v[36:39]
	v_mfma_f32_16x16x128_f8f6f4 v[32:35], v[24:31], v[240:247], v[32:35]
	s_setprio 0
	s_barrier
	s_add_i32 s41, s41, 2
	s_add_u32 s10, s10, 0x100
	s_addc_u32 s11, s11, 0
	s_add_u32 s34, s34, 0x100
	s_addc_u32 s35, s35, 0
	s_cmp_gt_u32 s41, 13
	s_cbranch_scc0 .LBB0_1122
